# MLA loop: the six packed f32 adds of the row sums split into scalar pairs
# speedup vs baseline: 1.0031x; 1.0031x over previous
.LBB0_2730:
	v_exp_f32_e32 v80, v80
	v_exp_f32_e32 v81, v81
	v_exp_f32_e32 v82, v82
	v_exp_f32_e32 v83, v83
	v_exp_f32_e32 v201, v84
	v_exp_f32_e32 v202, v85
	v_mov_b32_e32 v84, v86
	v_mov_b32_e32 v86, v88
	v_mov_b32_e32 v88, v90
	v_mov_b32_e32 v90, v92
	v_mov_b32_e32 v92, v94
	v_exp_f32_e32 v94, v64
	v_add_f32_e32 v193, 0, v80
	v_exp_f32_e32 v203, v84
	v_mov_b32_e32 v84, v87
	v_mov_b32_e32 v87, v89
	v_mov_b32_e32 v89, v91
	v_mov_b32_e32 v91, v93
	v_mov_b32_e32 v93, v95
	v_exp_f32_e32 v95, v65
	s_mul_i32 s4, s13, 0x2400
	v_add_f32_e32 v195, 0, v81
	v_add_f32_e32 v193, v82, v193
	v_exp_f32_e32 v196, v66
	v_add_f32_e32 v195, v83, v195
	v_exp_f32_e32 v204, v84
	v_add_f32_e32 v84, v201, v193
	v_exp_f32_e32 v197, v67
	v_add_u32_e32 v193, s4, v159
	v_add_f32_e32 v85, v202, v195
	v_exp_f32_e32 v198, v68
	v_add_u32_e32 v195, 0x9800, v193
	v_exp_f32_e32 v199, v69
	ds_read_b64 v[64:65], v195 offset:1024
	ds_read_b64 v[66:67], v195 offset:1040
	v_add_u32_e32 v193, 0xa800, v193
	v_exp_f32_e32 v200, v70
	v_mov_b32_e32 v205, v71
	v_cvt_pk_bf16_f32 v68, v80, v81
	v_cvt_pk_bf16_f32 v69, v82, v83
	v_cvt_pk_bf16_f32 v70, v201, v202
	v_cvt_pk_bf16_f32 v71, v203, v204
	ds_read_b64 v[80:81], v193 offset:1536
	ds_read_b64 v[82:83], v193 offset:1552
	v_add_f32_e32 v84, v203, v84
	s_waitcnt lgkmcnt(2)
	v_mfma_f32_32x32x16_bf16 v[16:31], v[64:67], v[68:71], v[16:31]
	v_exp_f32_e32 v202, v72
	v_exp_f32_e32 v203, v73
	ds_read_b64 v[64:65], v195 offset:1056
	ds_read_b64 v[66:67], v195 offset:1072
	v_exp_f32_e32 v86, v86
	v_exp_f32_e32 v87, v87
	v_exp_f32_e32 v88, v88
	v_exp_f32_e32 v89, v89
	v_exp_f32_e32 v90, v90
	v_exp_f32_e32 v91, v91
	v_exp_f32_e32 v92, v92
	v_exp_f32_e32 v93, v93
	s_waitcnt lgkmcnt(2)
	v_mfma_f32_32x32x16_bf16 v[0:15], v[80:83], v[68:71], v[0:15]
	v_exp_f32_e32 v80, v74
	v_mov_b32_e32 v81, v75
	ds_read_b64 v[72:73], v193 offset:1568
	ds_read_b64 v[74:75], v193 offset:1584
	v_cvt_pk_bf16_f32 v68, v86, v87
	v_cvt_pk_bf16_f32 v69, v88, v89
	v_cvt_pk_bf16_f32 v70, v90, v91
	v_cvt_pk_bf16_f32 v71, v92, v93
	v_exp_f32_e32 v201, v205
	v_add_f32_e32 v85, v204, v85
	s_waitcnt lgkmcnt(2)
	v_mfma_f32_32x32x16_bf16 v[16:31], v[64:67], v[68:71], v[16:31]
	v_exp_f32_e32 v76, v76
	v_exp_f32_e32 v77, v77
	ds_read_b64 v[64:65], v195 offset:1088
	ds_read_b64 v[66:67], v195 offset:1104
	s_waitcnt lgkmcnt(2)
	v_mfma_f32_32x32x16_bf16 v[0:15], v[72:75], v[68:71], v[0:15]
	ds_read_b64 v[72:73], v193 offset:1600
	ds_read_b64 v[74:75], v193 offset:1616
	v_cvt_pk_bf16_f32 v68, v94, v95
	v_cvt_pk_bf16_f32 v69, v196, v197
	v_cvt_pk_bf16_f32 v70, v198, v199
	v_cvt_pk_bf16_f32 v71, v200, v201
	v_exp_f32_e32 v81, v81
	v_exp_f32_e32 v78, v78
	s_waitcnt lgkmcnt(2)
	v_mfma_f32_32x32x16_bf16 v[16:31], v[64:67], v[68:71], v[16:31]
	v_add_f32_e64 v64, v86, v84
	v_add_f32_e64 v65, v87, v85
	v_exp_f32_e32 v79, v79
	v_add_f32_e32 v64, v88, v64
	v_add_f32_e32 v65, v89, v65
	s_add_i32 s16, s16, 2
	v_add_f32_e32 v64, v90, v64
	v_add_f32_e32 v65, v91, v65
	v_add_f32_e32 v64, v92, v64
	v_add_f32_e32 v65, v93, v65
	s_waitcnt lgkmcnt(0)
	v_mfma_f32_32x32x16_bf16 v[0:15], v[72:75], v[68:71], v[0:15]
	v_add_f32_e64 v82, v94, v64
	v_add_f32_e64 v83, v95, v65
	ds_read_b64 v[64:65], v195 offset:1120
	ds_read_b64 v[66:67], v195 offset:1136
	ds_read_b64 v[72:73], v193 offset:1632
	ds_read_b64 v[74:75], v193 offset:1648
	v_add_f32_e64 v68, v196, v82
	v_add_f32_e64 v69, v197, v83
	v_cvt_pk_bf16_f32 v70, v76, v77
	v_add_f32_e32 v82, v198, v68
	v_add_f32_e32 v83, v199, v69
	v_cvt_pk_bf16_f32 v68, v202, v203
	v_cvt_pk_bf16_f32 v69, v80, v81
	v_cvt_pk_bf16_f32 v71, v78, v79
	s_cmp_ge_u32 s18, s8
	s_waitcnt lgkmcnt(2)
	v_mfma_f32_32x32x16_bf16 v[16:31], v[64:67], v[68:71], v[16:31]
	v_add_f32_e64 v64, v200, v82
	v_add_f32_e64 v65, v201, v83
	v_add_f32_e64 v64, v202, v64
	v_add_f32_e64 v65, v203, v65
	v_add_f32_e32 v64, v80, v64
	v_add_f32_e32 v65, v81, v65
	s_nop 0
	v_add_f32_e32 v64, v76, v64
	v_add_f32_e32 v65, v77, v65
	s_waitcnt lgkmcnt(0)
	v_mfma_f32_32x32x16_bf16 v[0:15], v[72:75], v[68:71], v[0:15]
	v_add_f32_e64 v64, v78, v64
	v_add_f32_e64 v65, v79, v65
	v_add_f32_e32 v64, v64, v65
	v_add_f32_e32 v192, v192, v64
	s_cbranch_scc1 .LBB0_2693
	s_mov_b32 s4, s13
	s_mov_b32 s13, s12
	s_mov_b32 s12, s17
	s_branch .LBB0_2710
